# P3 stage D: 12 LDS reads per 8-k step of the two 32x32x32 f32 products issued together with counted lgkmcnt (was a wait per read pair); on top of NSA sink+epilogues
# speedup vs baseline: 1.0051x; 1.0051x over previous
.LBB0_622:
	v_add_u32_e32 v7, v240, v6
	v_add_u32_e32 v12, v240, v5
	v_add_u32_e32 v168, 0x13a00, v7
	v_add_u32_e32 v169, 0x18400, v12
	v_add_u32_e32 v170, 0x18840, v12
	ds_read2_b32 v[22:23], v168 offset0:0 offset1:1
	ds_read2_b32 v[30:31], v169 offset0:0 offset1:1
	ds_read2_b32 v[32:33], v169 offset0:68 offset1:69
	ds_read2_b32 v[24:25], v168 offset0:2 offset1:3
	ds_read2_b32 v[34:35], v169 offset0:136 offset1:137
	ds_read2_b32 v[36:37], v169 offset0:204 offset1:205
	ds_read2_b32 v[26:27], v168 offset0:4 offset1:5
	ds_read2_b32 v[160:161], v170 offset0:0 offset1:1
	ds_read2_b32 v[162:163], v170 offset0:68 offset1:69
	ds_read2_b32 v[28:29], v168 offset0:6 offset1:7
	ds_read2_b32 v[164:165], v170 offset0:136 offset1:137
	ds_read2_b32 v[166:167], v170 offset0:204 offset1:205
	s_add_i32 s9, s9, -8
	v_add_u32_e32 v6, 32, v6
	v_add_u32_e32 v5, 0x880, v5
	s_cmp_eq_u32 s9, 0
	s_waitcnt lgkmcnt(10)
	v_pk_fma_f32 v[2:3], v[22:23], v[30:31], v[2:3] op_sel_hi:[0,1,1]
	s_waitcnt lgkmcnt(9)
	v_pk_fma_f32 v[2:3], v[22:23], v[32:33], v[2:3] op_sel:[1,0,0]
	s_waitcnt lgkmcnt(7)
	v_pk_fma_f32 v[2:3], v[24:25], v[34:35], v[2:3] op_sel_hi:[0,1,1]
	s_waitcnt lgkmcnt(6)
	v_pk_fma_f32 v[2:3], v[24:25], v[36:37], v[2:3] op_sel:[1,0,0]
	s_waitcnt lgkmcnt(4)
	v_pk_fma_f32 v[2:3], v[26:27], v[160:161], v[2:3] op_sel_hi:[0,1,1]
	s_waitcnt lgkmcnt(3)
	v_pk_fma_f32 v[2:3], v[26:27], v[162:163], v[2:3] op_sel:[1,0,0]
	s_waitcnt lgkmcnt(1)
	v_pk_fma_f32 v[2:3], v[28:29], v[164:165], v[2:3] op_sel_hi:[0,1,1]
	s_waitcnt lgkmcnt(0)
	v_pk_fma_f32 v[2:3], v[28:29], v[166:167], v[2:3] op_sel:[1,0,0]
	s_cbranch_scc0 .LBB0_622
	v_add_u32_e32 v5, v240, v230
	s_mov_b32 s9, 0x1c800
	v_add3_u32 v5, v5, v239, s9
	ds_write2_b32 v5, v2, v3 offset1:1
	v_mov_b32_e32 v2, 0
	s_mov_b32 s9, 32
	v_mov_b32_e32 v5, v159
	v_mov_b32_e32 v6, v229
	v_mov_b32_e32 v3, v2
	s_waitcnt lgkmcnt(0)
	s_barrier
.LBB0_624:
	v_add_u32_e32 v7, v240, v6
	v_add_u32_e32 v12, v240, v5
	v_add_u32_e32 v168, 0x1a680, v7
	v_add_u32_e32 v169, 0x1c800, v12
	ds_read2_b32 v[22:23], v168 offset0:0 offset1:1
	ds_read2_b32 v[30:31], v169 offset0:0 offset1:1
	ds_read2_b32 v[32:33], v169 offset0:34 offset1:35
	ds_read2_b32 v[24:25], v168 offset0:2 offset1:3
	ds_read2_b32 v[34:35], v169 offset0:68 offset1:69
	ds_read2_b32 v[36:37], v169 offset0:102 offset1:103
	ds_read2_b32 v[26:27], v168 offset0:4 offset1:5
	ds_read2_b32 v[160:161], v169 offset0:136 offset1:137
	ds_read2_b32 v[162:163], v169 offset0:170 offset1:171
	ds_read2_b32 v[28:29], v168 offset0:6 offset1:7
	ds_read2_b32 v[164:165], v169 offset0:204 offset1:205
	ds_read2_b32 v[166:167], v169 offset0:238 offset1:239
	s_add_i32 s9, s9, -8
	v_add_u32_e32 v6, 32, v6
	v_add_u32_e32 v5, 0x440, v5
	s_cmp_lg_u32 s9, 0
	s_waitcnt lgkmcnt(10)
	v_pk_fma_f32 v[2:3], v[22:23], v[30:31], v[2:3] op_sel_hi:[0,1,1]
	s_waitcnt lgkmcnt(9)
	v_pk_fma_f32 v[2:3], v[22:23], v[32:33], v[2:3] op_sel:[1,0,0]
	s_waitcnt lgkmcnt(7)
	v_pk_fma_f32 v[2:3], v[24:25], v[34:35], v[2:3] op_sel_hi:[0,1,1]
	s_waitcnt lgkmcnt(6)
	v_pk_fma_f32 v[2:3], v[24:25], v[36:37], v[2:3] op_sel:[1,0,0]
	s_waitcnt lgkmcnt(4)
	v_pk_fma_f32 v[2:3], v[26:27], v[160:161], v[2:3] op_sel_hi:[0,1,1]
	s_waitcnt lgkmcnt(3)
	v_pk_fma_f32 v[2:3], v[26:27], v[162:163], v[2:3] op_sel:[1,0,0]
	s_waitcnt lgkmcnt(1)
	v_pk_fma_f32 v[2:3], v[28:29], v[164:165], v[2:3] op_sel_hi:[0,1,1]
	s_waitcnt lgkmcnt(0)
	v_pk_fma_f32 v[2:3], v[28:29], v[166:167], v[2:3] op_sel:[1,0,0]
	s_cbranch_scc1 .LBB0_624
	v_add_u32_e32 v5, v4, v229
	s_movk_i32 s9, 0x2200
	v_pk_add_f32 v[2:3], v[2:3], 0 neg_lo:[1,1] neg_hi:[1,1]
	v_add3_u32 v5, v5, v239, s9
	ds_write2_b32 v5, v2, v3 offset1:1
	v_lshlrev_b32_e32 v2, 2, v231
	v_add3_u32 v6, v4, v185, v2
	s_waitcnt lgkmcnt(0)
	s_barrier
	ds_read_b128 v[2:5], v6
	ds_read_b128 v[6:9], v6 offset:16
	v_add_u32_e32 v10, 0x15c00, v240
	v_add3_u32 v42, v240, v233, v234
	v_lshl_add_u64 v[164:165], v[120:121], 0, s[16:17]
	s_waitcnt lgkmcnt(1)
	v_cvt_pk_bf16_f32 v2, v2, v3
	v_cvt_pk_bf16_f32 v3, v4, v5
	s_waitcnt lgkmcnt(0)
	v_cvt_pk_bf16_f32 v4, v6, v7
	v_lshlrev_b32_e32 v6, 1, v231
	v_mul_u32_u24_e32 v7, 0x90, v184
	v_cvt_pk_bf16_f32 v5, v8, v9
	v_add3_u32 v6, v10, v7, v6
	ds_write_b128 v6, v[2:5]
	v_mul_u32_u24_e32 v2, 0x90, v152
	v_add3_u32 v2, v10, v155, v2
	s_waitcnt lgkmcnt(0)
	s_barrier
	ds_read_b128 v[18:21], v2
	ds_read_b128 v[22:25], v2 offset:64
	ds_read_b128 v[26:29], v2 offset:2304
	ds_read_b128 v[30:33], v2 offset:2368
	ds_read_b128 v[14:17], v2 offset:4608
	ds_read_b128 v[10:13], v2 offset:4672
	ds_read_b128 v[6:9], v2 offset:6912
	ds_read_b128 v[2:5], v2 offset:6976
	ds_read_b128 v[34:37], v42 offset:53248
	ds_read_b128 v[142:145], v42 offset:53312
	s_waitcnt lgkmcnt(1)
	v_mfma_f32_16x16x32_bf16 v[160:163], v[18:21], v[34:37], 0
	s_add_u32 s16, s24, s16
	s_addc_u32 s17, s25, s17
	s_waitcnt lgkmcnt(0)
	v_mfma_f32_16x16x32_bf16 v[160:163], v[22:25], v[142:145], v[160:163]
	s_nop 7
	v_cvt_pk_bf16_f32 v160, v160, v161
	v_cvt_pk_bf16_f32 v161, v162, v163
	global_store_dwordx2 v[164:165], v[160:161], off
	v_mfma_f32_16x16x32_bf16 v[160:163], v[26:29], v[34:37], 0
	v_mfma_f32_16x16x32_bf16 v[160:163], v[30:33], v[142:145], v[160:163]
	s_nop 7
	v_cvt_pk_bf16_f32 v160, v160, v161
	v_cvt_pk_bf16_f32 v161, v162, v163
	global_store_dwordx2 v[164:165], v[160:161], off offset:1024
	v_mfma_f32_16x16x32_bf16 v[160:163], v[14:17], v[34:37], 0
	v_mfma_f32_16x16x32_bf16 v[34:37], v[6:9], v[34:37], 0
	v_mfma_f32_16x16x32_bf16 v[160:163], v[10:13], v[142:145], v[160:163]
	v_mfma_f32_16x16x32_bf16 v[34:37], v[2:5], v[142:145], v[34:37]
	s_nop 6
	v_cvt_pk_bf16_f32 v160, v160, v161
	v_cvt_pk_bf16_f32 v161, v162, v163
	v_cvt_pk_bf16_f32 v34, v34, v35
	v_cvt_pk_bf16_f32 v35, v36, v37
	global_store_dwordx2 v[164:165], v[160:161], off offset:2048
	global_store_dwordx2 v[164:165], v[34:35], off offset:3072
	ds_read_b128 v[34:37], v42 offset:34816
	ds_read_b128 v[142:145], v42 offset:34880
	s_waitcnt lgkmcnt(1)
	v_mfma_f32_16x16x32_bf16 v[18:21], v[34:37], v[18:21], 0
	s_waitcnt lgkmcnt(0)
	v_mfma_f32_16x16x32_bf16 v[18:21], v[142:145], v[22:25], v[18:21]
	v_mfma_f32_16x16x32_bf16 v[14:17], v[34:37], v[14:17], 0
	v_mfma_f32_16x16x32_bf16 v[6:9], v[34:37], v[6:9], 0
	s_nop 5
	v_cvt_pk_bf16_f32 v18, v18, v19
	v_cvt_pk_bf16_f32 v19, v20, v21
	v_lshl_add_u64 v[20:21], v[122:123], 1, s[16:17]
	global_store_dwordx2 v[20:21], v[18:19], off
	v_mfma_f32_16x16x32_bf16 v[18:21], v[34:37], v[26:29], 0
	v_mfma_f32_16x16x32_bf16 v[18:21], v[142:145], v[30:33], v[18:21]
	v_mfma_f32_16x16x32_bf16 v[10:13], v[142:145], v[10:13], v[14:17]
	v_mfma_f32_16x16x32_bf16 v[2:5], v[142:145], v[2:5], v[6:9]
	s_nop 5
	v_cvt_pk_bf16_f32 v18, v18, v19
	v_cvt_pk_bf16_f32 v19, v20, v21
	v_lshl_add_u64 v[20:21], v[124:125], 1, s[16:17]
	v_cvt_pk_bf16_f32 v10, v10, v11
	v_cvt_pk_bf16_f32 v11, v12, v13
	v_lshl_add_u64 v[12:13], v[126:127], 1, s[16:17]
	v_cvt_pk_bf16_f32 v2, v2, v3
	v_cvt_pk_bf16_f32 v3, v4, v5
	v_lshl_add_u64 v[4:5], v[128:129], 1, s[16:17]
	global_store_dwordx2 v[20:21], v[18:19], off
	global_store_dwordx2 v[12:13], v[10:11], off
	global_store_dwordx2 v[4:5], v[2:3], off
	s_barrier
	s_branch .LBB0_394
